# small-tile GEMM tail K-loops rewritten: 2-deep global prefetch (two staging register sets, unrolled x2) and batched LDS fragment reads
# baseline (speedup 1.0000x reference)
.LBB0_1033:
.LBB0_1034:
	v_lshlrev_b32_e32 v38, 1, v170
	v_lshlrev_b32_e32 v172, 1, v61
	v_add_u32_e32 v174, v172, v69
	v_add_u32_e32 v173, v172, v68
	v_add_u32_e32 v172, v172, v67
	v_add_u32_e32 v175, v62, v38
	v_add_u32_e32 v176, v38, v70
	v_add_u32_e32 v177, v38, v71
	v_add_u32_e32 v178, v38, v72
	global_load_dwordx4 v[84:87], v[50:51], off
	global_load_dwordx4 v[88:91], v[52:53], off
	global_load_dwordx4 v[92:95], v[54:55], off
	global_load_dwordx4 v[96:99], v[56:57], off
	global_load_dwordx4 v[100:103], v[58:59], off
	s_mov_b32 s18, 0x100
	s_mov_b32 s19, 0
.Ltail0_loop:
	s_waitcnt vmcnt(5)
	ds_write_b128 v172, v[10:13] offset:0
	s_and_saveexec_b64 s[10:11], s[6:7]
	ds_write_b128 v173, v[14:17] offset:0
	s_or_b64 exec, exec, s[10:11]
	s_and_saveexec_b64 s[10:11], s[8:9]
	ds_write_b128 v174, v[18:21] offset:0
	s_or_b64 exec, exec, s[10:11]
	ds_write_b128 v172, v[26:29] offset:43520
	ds_write_b128 v173, v[22:25] offset:43520
	s_cmpk_lt_u32 s18, 0x1500
	s_cbranch_scc0 .Ltail0_np0
	v_lshl_add_u64 v[180:181], v[50:51], 0, s[18:19]
	global_load_dwordx4 v[10:13], v[180:181], off
	v_lshl_add_u64 v[180:181], v[52:53], 0, s[18:19]
	global_load_dwordx4 v[14:17], v[180:181], off
	v_lshl_add_u64 v[180:181], v[54:55], 0, s[18:19]
	global_load_dwordx4 v[18:21], v[180:181], off
	v_lshl_add_u64 v[180:181], v[56:57], 0, s[18:19]
	global_load_dwordx4 v[26:29], v[180:181], off
	v_lshl_add_u64 v[180:181], v[58:59], 0, s[18:19]
	global_load_dwordx4 v[22:25], v[180:181], off
.Ltail0_np0:
	s_add_u32 s18, s18, 0x100
	s_waitcnt lgkmcnt(0)
	s_barrier
	ds_read_b128 v[104:107], v175 offset:43520
	ds_read_b128 v[108:111], v175 offset:43584
	ds_read_b128 v[112:115], v175 offset:43648
	ds_read_b128 v[116:119], v175 offset:43712
	ds_read_b128 v[120:123], v176 offset:0
	ds_read_b128 v[124:127], v176 offset:64
	ds_read_b128 v[128:131], v176 offset:128
	ds_read_b128 v[132:135], v176 offset:192
	ds_read_b128 v[136:139], v177 offset:0
	ds_read_b128 v[140:143], v177 offset:64
	ds_read_b128 v[144:147], v177 offset:128
	ds_read_b128 v[148:151], v177 offset:192
	s_andn2_b64 vcc, exec, s[14:15]
	s_cbranch_vccnz .Ltail0_r0
	ds_read_b128 v[152:155], v178 offset:17408
	ds_read_b128 v[156:159], v178 offset:17472
	ds_read_b128 v[160:163], v178 offset:17536
	ds_read_b128 v[164:167], v178 offset:17600
.Ltail0_r0:
	s_waitcnt lgkmcnt(0)
	v_mfma_f32_16x16x32_bf16 v[30:33], v[104:107], v[120:123], v[30:33]
	v_mfma_f32_16x16x32_bf16 v[6:9], v[104:107], v[136:139], v[6:9]
	v_mfma_f32_16x16x32_bf16 v[30:33], v[108:111], v[124:127], v[30:33]
	v_mfma_f32_16x16x32_bf16 v[6:9], v[108:111], v[140:143], v[6:9]
	v_mfma_f32_16x16x32_bf16 v[30:33], v[112:115], v[128:131], v[30:33]
	v_mfma_f32_16x16x32_bf16 v[6:9], v[112:115], v[144:147], v[6:9]
	v_mfma_f32_16x16x32_bf16 v[30:33], v[116:119], v[132:135], v[30:33]
	v_mfma_f32_16x16x32_bf16 v[6:9], v[116:119], v[148:151], v[6:9]
	s_andn2_b64 vcc, exec, s[14:15]
	s_cbranch_vccnz .Ltail0_m0
	v_mfma_f32_16x16x32_bf16 v[2:5], v[104:107], v[152:155], v[2:5]
	v_mfma_f32_16x16x32_bf16 v[2:5], v[108:111], v[156:159], v[2:5]
	v_mfma_f32_16x16x32_bf16 v[2:5], v[112:115], v[160:163], v[2:5]
	v_mfma_f32_16x16x32_bf16 v[2:5], v[116:119], v[164:167], v[2:5]
.Ltail0_m0:
	s_waitcnt vmcnt(5)
	s_cmpk_lt_u32 s18, 0x1600
	s_cbranch_scc1 .Ltail0_w1
	s_waitcnt vmcnt(0)
.Ltail0_w1:
	ds_write_b128 v172, v[84:87] offset:21760
	s_and_saveexec_b64 s[10:11], s[6:7]
	ds_write_b128 v173, v[88:91] offset:21760
	s_or_b64 exec, exec, s[10:11]
	s_and_saveexec_b64 s[10:11], s[8:9]
	ds_write_b128 v174, v[92:95] offset:21760
	s_or_b64 exec, exec, s[10:11]
	ds_write_b128 v172, v[96:99] offset:60928
	ds_write_b128 v173, v[100:103] offset:60928
	s_cmpk_lt_u32 s18, 0x1500
	s_cbranch_scc0 .Ltail0_np1
	v_lshl_add_u64 v[180:181], v[50:51], 0, s[18:19]
	global_load_dwordx4 v[84:87], v[180:181], off
	v_lshl_add_u64 v[180:181], v[52:53], 0, s[18:19]
	global_load_dwordx4 v[88:91], v[180:181], off
	v_lshl_add_u64 v[180:181], v[54:55], 0, s[18:19]
	global_load_dwordx4 v[92:95], v[180:181], off
	v_lshl_add_u64 v[180:181], v[56:57], 0, s[18:19]
	global_load_dwordx4 v[96:99], v[180:181], off
	v_lshl_add_u64 v[180:181], v[58:59], 0, s[18:19]
	global_load_dwordx4 v[100:103], v[180:181], off
.Ltail0_np1:
	s_add_u32 s18, s18, 0x100
	s_waitcnt lgkmcnt(0)
	s_barrier
	ds_read_b128 v[104:107], v175 offset:60928
	ds_read_b128 v[108:111], v175 offset:60992
	ds_read_b128 v[112:115], v175 offset:61056
	ds_read_b128 v[116:119], v175 offset:61120
	ds_read_b128 v[120:123], v176 offset:21760
	ds_read_b128 v[124:127], v176 offset:21824
	ds_read_b128 v[128:131], v176 offset:21888
	ds_read_b128 v[132:135], v176 offset:21952
	ds_read_b128 v[136:139], v177 offset:21760
	ds_read_b128 v[140:143], v177 offset:21824
	ds_read_b128 v[144:147], v177 offset:21888
	ds_read_b128 v[148:151], v177 offset:21952
	s_andn2_b64 vcc, exec, s[14:15]
	s_cbranch_vccnz .Ltail0_r1
	ds_read_b128 v[152:155], v178 offset:39168
	ds_read_b128 v[156:159], v178 offset:39232
	ds_read_b128 v[160:163], v178 offset:39296
	ds_read_b128 v[164:167], v178 offset:39360

.Ltail0_m1:
	s_cmpk_lt_u32 s18, 0x1700
	s_cbranch_scc1 .Ltail0_loop
	s_movk_i32 s18, 0x1600
	s_mov_b32 s19, 0
	s_movk_i32 s20, 0x16
	v_cndmask_b32_e64 v80, 0, 1, s[14:15]
	s_nop 1
	v_cmp_ne_u32_e64 s[10:11], 1, v80
	s_nop 7

.LBB0_2881:
.LBB0_2882:
	v_lshlrev_b32_e32 v168, 1, v59
	v_add_u32_e32 v170, v168, v67
	v_add_u32_e32 v169, v168, v66
	v_add_u32_e32 v168, v168, v65
	v_add_u32_e32 v171, v60, v38
	v_add_u32_e32 v172, v38, v68
	v_add_u32_e32 v173, v38, v69
	v_add_u32_e32 v174, v38, v70
	global_load_dwordx4 v[84:87], v[48:49], off
	global_load_dwordx4 v[88:91], v[50:51], off
	global_load_dwordx4 v[92:95], v[52:53], off
	global_load_dwordx4 v[96:99], v[54:55], off
	global_load_dwordx4 v[100:103], v[56:57], off
	s_mov_b32 s10, 0x100
	s_mov_b32 s11, 0
.Ltail1_loop:
	s_waitcnt vmcnt(5)
	ds_write_b128 v168, v[6:9] offset:0
	s_and_saveexec_b64 s[6:7], s[0:1]
	ds_write_b128 v169, v[10:13] offset:0
	s_or_b64 exec, exec, s[6:7]
	s_and_saveexec_b64 s[6:7], s[4:5]
	ds_write_b128 v170, v[14:17] offset:0
	s_or_b64 exec, exec, s[6:7]
	ds_write_b128 v168, v[18:21] offset:43520
	ds_write_b128 v169, v[22:25] offset:43520
	s_cmpk_lt_u32 s10, 0x700
	s_cbranch_scc0 .Ltail1_np0
	v_lshl_add_u64 v[176:177], v[48:49], 0, s[10:11]
	global_load_dwordx4 v[6:9], v[176:177], off
	v_lshl_add_u64 v[176:177], v[50:51], 0, s[10:11]
	global_load_dwordx4 v[10:13], v[176:177], off
	v_lshl_add_u64 v[176:177], v[52:53], 0, s[10:11]
	global_load_dwordx4 v[14:17], v[176:177], off
	v_lshl_add_u64 v[176:177], v[54:55], 0, s[10:11]
	global_load_dwordx4 v[18:21], v[176:177], off
	v_lshl_add_u64 v[176:177], v[56:57], 0, s[10:11]
	global_load_dwordx4 v[22:25], v[176:177], off
.Ltail1_np0:
	s_add_u32 s10, s10, 0x100
	s_waitcnt lgkmcnt(0)
	s_barrier
	ds_read_b128 v[104:107], v171 offset:43520
	ds_read_b128 v[108:111], v171 offset:43584
	ds_read_b128 v[112:115], v171 offset:43648
	ds_read_b128 v[116:119], v171 offset:43712
	ds_read_b128 v[120:123], v172 offset:0
	ds_read_b128 v[124:127], v172 offset:64
	ds_read_b128 v[128:131], v172 offset:128
	ds_read_b128 v[132:135], v172 offset:192
	ds_read_b128 v[136:139], v173 offset:0
	ds_read_b128 v[140:143], v173 offset:64
	ds_read_b128 v[144:147], v173 offset:128
	ds_read_b128 v[148:151], v173 offset:192
	s_andn2_b64 vcc, exec, s[8:9]
	s_cbranch_vccnz .Ltail1_r0
	ds_read_b128 v[152:155], v174 offset:17408
	ds_read_b128 v[156:159], v174 offset:17472
	ds_read_b128 v[160:163], v174 offset:17536
	ds_read_b128 v[164:167], v174 offset:17600
.Ltail1_r0:
	s_waitcnt lgkmcnt(0)
	v_mfma_f32_16x16x32_bf16 v[30:33], v[104:107], v[120:123], v[30:33]
	v_mfma_f32_16x16x32_bf16 v[26:29], v[104:107], v[136:139], v[26:29]
	v_mfma_f32_16x16x32_bf16 v[30:33], v[108:111], v[124:127], v[30:33]
	v_mfma_f32_16x16x32_bf16 v[26:29], v[108:111], v[140:143], v[26:29]
	v_mfma_f32_16x16x32_bf16 v[30:33], v[112:115], v[128:131], v[30:33]
	v_mfma_f32_16x16x32_bf16 v[26:29], v[112:115], v[144:147], v[26:29]
	v_mfma_f32_16x16x32_bf16 v[30:33], v[116:119], v[132:135], v[30:33]
	v_mfma_f32_16x16x32_bf16 v[26:29], v[116:119], v[148:151], v[26:29]
	s_andn2_b64 vcc, exec, s[8:9]
	s_cbranch_vccnz .Ltail1_m0
	v_mfma_f32_16x16x32_bf16 v[2:5], v[104:107], v[152:155], v[2:5]
	v_mfma_f32_16x16x32_bf16 v[2:5], v[108:111], v[156:159], v[2:5]
	v_mfma_f32_16x16x32_bf16 v[2:5], v[112:115], v[160:163], v[2:5]
	v_mfma_f32_16x16x32_bf16 v[2:5], v[116:119], v[164:167], v[2:5]
.Ltail1_m0:
	s_waitcnt vmcnt(5)
	s_cmpk_lt_u32 s10, 0x800
	s_cbranch_scc1 .Ltail1_w1
	s_waitcnt vmcnt(0)
.Ltail1_w1:
	ds_write_b128 v168, v[84:87] offset:21760
	s_and_saveexec_b64 s[6:7], s[0:1]
	ds_write_b128 v169, v[88:91] offset:21760
	s_or_b64 exec, exec, s[6:7]
	s_and_saveexec_b64 s[6:7], s[4:5]
	ds_write_b128 v170, v[92:95] offset:21760
	s_or_b64 exec, exec, s[6:7]
	ds_write_b128 v168, v[96:99] offset:60928
	ds_write_b128 v169, v[100:103] offset:60928
	s_cmpk_lt_u32 s10, 0x700
	s_cbranch_scc0 .Ltail1_np1
	v_lshl_add_u64 v[176:177], v[48:49], 0, s[10:11]
	global_load_dwordx4 v[84:87], v[176:177], off
	v_lshl_add_u64 v[176:177], v[50:51], 0, s[10:11]
	global_load_dwordx4 v[88:91], v[176:177], off
	v_lshl_add_u64 v[176:177], v[52:53], 0, s[10:11]
	global_load_dwordx4 v[92:95], v[176:177], off
	v_lshl_add_u64 v[176:177], v[54:55], 0, s[10:11]
	global_load_dwordx4 v[96:99], v[176:177], off
	v_lshl_add_u64 v[176:177], v[56:57], 0, s[10:11]
	global_load_dwordx4 v[100:103], v[176:177], off
.Ltail1_np1:
	s_add_u32 s10, s10, 0x100
	s_waitcnt lgkmcnt(0)
	s_barrier
	ds_read_b128 v[104:107], v171 offset:60928
	ds_read_b128 v[108:111], v171 offset:60992
	ds_read_b128 v[112:115], v171 offset:61056
	ds_read_b128 v[116:119], v171 offset:61120
	ds_read_b128 v[120:123], v172 offset:21760
	ds_read_b128 v[124:127], v172 offset:21824
	ds_read_b128 v[128:131], v172 offset:21888
	ds_read_b128 v[132:135], v172 offset:21952
	ds_read_b128 v[136:139], v173 offset:21760
	ds_read_b128 v[140:143], v173 offset:21824
	ds_read_b128 v[144:147], v173 offset:21888
	ds_read_b128 v[148:151], v173 offset:21952
	s_andn2_b64 vcc, exec, s[8:9]
	s_cbranch_vccnz .Ltail1_r1
	ds_read_b128 v[152:155], v174 offset:39168
	ds_read_b128 v[156:159], v174 offset:39232
	ds_read_b128 v[160:163], v174 offset:39296
	ds_read_b128 v[164:167], v174 offset:39360

.Ltail1_m1:
	s_cmpk_lt_u32 s10, 0x900
	s_cbranch_scc1 .Ltail1_loop
	s_movk_i32 s10, 0x800
	s_mov_b32 s11, 0
	s_movk_i32 s18, 0x8
	v_cndmask_b32_e64 v75, 0, 1, s[8:9]
	s_nop 1
	v_cmp_ne_u32_e64 s[6:7], 1, v75
	s_nop 7

.LBB0_2929:
.LBB0_2930:
	v_lshlrev_b32_e32 v74, 1, v160
	v_lshlrev_b32_e32 v172, 1, v59
	v_add_u32_e32 v174, v172, v67
	v_add_u32_e32 v173, v172, v66
	v_add_u32_e32 v172, v172, v65
	v_add_u32_e32 v175, v60, v74
	v_add_u32_e32 v176, v74, v68
	v_add_u32_e32 v177, v74, v69
	v_add_u32_e32 v178, v74, v70
	global_load_dwordx4 v[84:87], v[48:49], off
	global_load_dwordx4 v[88:91], v[50:51], off
	global_load_dwordx4 v[92:95], v[52:53], off
	global_load_dwordx4 v[96:99], v[54:55], off
	global_load_dwordx4 v[100:103], v[56:57], off
	s_mov_b32 s8, 0x100
	s_mov_b32 s9, 0
.Ltail2_loop:
	s_waitcnt vmcnt(5)
	ds_write_b128 v172, v[6:9] offset:0
	s_and_saveexec_b64 s[6:7], s[0:1]
	ds_write_b128 v173, v[10:13] offset:0
	s_or_b64 exec, exec, s[6:7]
	s_and_saveexec_b64 s[6:7], s[4:5]
	ds_write_b128 v174, v[14:17] offset:0
	s_or_b64 exec, exec, s[6:7]
	ds_write_b128 v172, v[18:21] offset:43520
	ds_write_b128 v173, v[22:25] offset:43520
	s_cmpk_lt_u32 s8, 0x700
	s_cbranch_scc0 .Ltail2_np0
	v_lshl_add_u64 v[180:181], v[48:49], 0, s[8:9]
	global_load_dwordx4 v[6:9], v[180:181], off
	v_lshl_add_u64 v[180:181], v[50:51], 0, s[8:9]
	global_load_dwordx4 v[10:13], v[180:181], off
	v_lshl_add_u64 v[180:181], v[52:53], 0, s[8:9]
	global_load_dwordx4 v[14:17], v[180:181], off
	v_lshl_add_u64 v[180:181], v[54:55], 0, s[8:9]
	global_load_dwordx4 v[18:21], v[180:181], off
	v_lshl_add_u64 v[180:181], v[56:57], 0, s[8:9]
	global_load_dwordx4 v[22:25], v[180:181], off
.Ltail2_np0:
	s_add_u32 s8, s8, 0x100
	s_waitcnt lgkmcnt(0)
	s_barrier
	ds_read_b128 v[104:107], v175 offset:43520
	ds_read_b128 v[108:111], v175 offset:43584
	ds_read_b128 v[112:115], v175 offset:43648
	ds_read_b128 v[116:119], v175 offset:43712
	ds_read_b128 v[120:123], v176 offset:0
	ds_read_b128 v[124:127], v176 offset:64
	ds_read_b128 v[128:131], v176 offset:128
	ds_read_b128 v[132:135], v176 offset:192
	ds_read_b128 v[136:139], v177 offset:0
	ds_read_b128 v[140:143], v177 offset:64
	ds_read_b128 v[144:147], v177 offset:128
	ds_read_b128 v[148:151], v177 offset:192
	s_andn2_b64 vcc, exec, s[16:17]
	s_cbranch_vccnz .Ltail2_r0
	ds_read_b128 v[152:155], v178 offset:17408
	ds_read_b128 v[156:159], v178 offset:17472
	ds_read_b128 v[164:167], v178 offset:17536
	ds_read_b128 v[168:171], v178 offset:17600
.Ltail2_r0:
	s_waitcnt lgkmcnt(0)
	v_mfma_f32_16x16x32_bf16 v[30:33], v[104:107], v[120:123], v[30:33]
	v_mfma_f32_16x16x32_bf16 v[26:29], v[104:107], v[136:139], v[26:29]
	v_mfma_f32_16x16x32_bf16 v[30:33], v[108:111], v[124:127], v[30:33]
	v_mfma_f32_16x16x32_bf16 v[26:29], v[108:111], v[140:143], v[26:29]
	v_mfma_f32_16x16x32_bf16 v[30:33], v[112:115], v[128:131], v[30:33]
	v_mfma_f32_16x16x32_bf16 v[26:29], v[112:115], v[144:147], v[26:29]
	v_mfma_f32_16x16x32_bf16 v[30:33], v[116:119], v[132:135], v[30:33]
	v_mfma_f32_16x16x32_bf16 v[26:29], v[116:119], v[148:151], v[26:29]
	s_andn2_b64 vcc, exec, s[16:17]
	s_cbranch_vccnz .Ltail2_m0
	v_mfma_f32_16x16x32_bf16 v[2:5], v[104:107], v[152:155], v[2:5]
	v_mfma_f32_16x16x32_bf16 v[2:5], v[108:111], v[156:159], v[2:5]
	v_mfma_f32_16x16x32_bf16 v[2:5], v[112:115], v[164:167], v[2:5]
	v_mfma_f32_16x16x32_bf16 v[2:5], v[116:119], v[168:171], v[2:5]
.Ltail2_m0:
	s_waitcnt vmcnt(5)
	s_cmpk_lt_u32 s8, 0x800
	s_cbranch_scc1 .Ltail2_w1
	s_waitcnt vmcnt(0)
.Ltail2_w1:
	ds_write_b128 v172, v[84:87] offset:21760
	s_and_saveexec_b64 s[6:7], s[0:1]
	ds_write_b128 v173, v[88:91] offset:21760
	s_or_b64 exec, exec, s[6:7]
	s_and_saveexec_b64 s[6:7], s[4:5]
	ds_write_b128 v174, v[92:95] offset:21760
	s_or_b64 exec, exec, s[6:7]
	ds_write_b128 v172, v[96:99] offset:60928
	ds_write_b128 v173, v[100:103] offset:60928
	s_cmpk_lt_u32 s8, 0x700
	s_cbranch_scc0 .Ltail2_np1
	v_lshl_add_u64 v[180:181], v[48:49], 0, s[8:9]
	global_load_dwordx4 v[84:87], v[180:181], off
	v_lshl_add_u64 v[180:181], v[50:51], 0, s[8:9]
	global_load_dwordx4 v[88:91], v[180:181], off
	v_lshl_add_u64 v[180:181], v[52:53], 0, s[8:9]
	global_load_dwordx4 v[92:95], v[180:181], off
	v_lshl_add_u64 v[180:181], v[54:55], 0, s[8:9]
	global_load_dwordx4 v[96:99], v[180:181], off
	v_lshl_add_u64 v[180:181], v[56:57], 0, s[8:9]
	global_load_dwordx4 v[100:103], v[180:181], off
.Ltail2_np1:
	s_add_u32 s8, s8, 0x100
	s_waitcnt lgkmcnt(0)
	s_barrier
	ds_read_b128 v[104:107], v175 offset:60928
	ds_read_b128 v[108:111], v175 offset:60992
	ds_read_b128 v[112:115], v175 offset:61056
	ds_read_b128 v[116:119], v175 offset:61120
	ds_read_b128 v[120:123], v176 offset:21760
	ds_read_b128 v[124:127], v176 offset:21824
	ds_read_b128 v[128:131], v176 offset:21888
	ds_read_b128 v[132:135], v176 offset:21952
	ds_read_b128 v[136:139], v177 offset:21760
	ds_read_b128 v[140:143], v177 offset:21824
	ds_read_b128 v[144:147], v177 offset:21888
	ds_read_b128 v[148:151], v177 offset:21952
	s_andn2_b64 vcc, exec, s[16:17]
	s_cbranch_vccnz .Ltail2_r1
	ds_read_b128 v[152:155], v178 offset:39168
	ds_read_b128 v[156:159], v178 offset:39232
	ds_read_b128 v[164:167], v178 offset:39296
	ds_read_b128 v[168:171], v178 offset:39360

.Ltail2_m1:
	s_cmpk_lt_u32 s8, 0x900
	s_cbranch_scc1 .Ltail2_loop
	s_movk_i32 s8, 0x800
	s_mov_b32 s9, 0
	s_movk_i32 s21, 0x8
	v_cndmask_b32_e64 v78, 0, 1, s[16:17]
	s_nop 1
	v_cmp_ne_u32_e64 s[6:7], 1, v78
	s_nop 7

.LBB0_3040:
.LBB0_3041:
	v_lshlrev_b32_e32 v168, 1, v59
	v_add_u32_e32 v170, v168, v67
	v_add_u32_e32 v169, v168, v66
	v_add_u32_e32 v168, v168, v65
	v_add_u32_e32 v171, v60, v38
	v_add_u32_e32 v172, v38, v68
	v_add_u32_e32 v173, v38, v69
	v_add_u32_e32 v174, v38, v70
	global_load_dwordx4 v[84:87], v[48:49], off
	global_load_dwordx4 v[88:91], v[50:51], off
	global_load_dwordx4 v[92:95], v[52:53], off
	global_load_dwordx4 v[96:99], v[54:55], off
	global_load_dwordx4 v[100:103], v[56:57], off
	s_mov_b32 s12, 0x100
	s_mov_b32 s13, 0
.Ltail3_loop:
	s_waitcnt vmcnt(5)
	ds_write_b128 v168, v[6:9] offset:0
	s_and_saveexec_b64 s[6:7], s[0:1]
	ds_write_b128 v169, v[10:13] offset:0
	s_or_b64 exec, exec, s[6:7]
	s_and_saveexec_b64 s[6:7], s[4:5]
	ds_write_b128 v170, v[14:17] offset:0
	s_or_b64 exec, exec, s[6:7]
	ds_write_b128 v168, v[18:21] offset:43520
	ds_write_b128 v169, v[22:25] offset:43520
	s_cmpk_lt_u32 s12, 0x700
	s_cbranch_scc0 .Ltail3_np0
	v_lshl_add_u64 v[176:177], v[48:49], 0, s[12:13]
	global_load_dwordx4 v[6:9], v[176:177], off
	v_lshl_add_u64 v[176:177], v[50:51], 0, s[12:13]
	global_load_dwordx4 v[10:13], v[176:177], off
	v_lshl_add_u64 v[176:177], v[52:53], 0, s[12:13]
	global_load_dwordx4 v[14:17], v[176:177], off
	v_lshl_add_u64 v[176:177], v[54:55], 0, s[12:13]
	global_load_dwordx4 v[18:21], v[176:177], off
	v_lshl_add_u64 v[176:177], v[56:57], 0, s[12:13]
	global_load_dwordx4 v[22:25], v[176:177], off
.Ltail3_np0:
	s_add_u32 s12, s12, 0x100
	s_waitcnt lgkmcnt(0)
	s_barrier
	ds_read_b128 v[104:107], v171 offset:43520
	ds_read_b128 v[108:111], v171 offset:43584
	ds_read_b128 v[112:115], v171 offset:43648
	ds_read_b128 v[116:119], v171 offset:43712
	ds_read_b128 v[120:123], v172 offset:0
	ds_read_b128 v[124:127], v172 offset:64
	ds_read_b128 v[128:131], v172 offset:128
	ds_read_b128 v[132:135], v172 offset:192
	ds_read_b128 v[136:139], v173 offset:0
	ds_read_b128 v[140:143], v173 offset:64
	ds_read_b128 v[144:147], v173 offset:128
	ds_read_b128 v[148:151], v173 offset:192
	s_andn2_b64 vcc, exec, s[10:11]
	s_cbranch_vccnz .Ltail3_r0
	ds_read_b128 v[152:155], v174 offset:17408
	ds_read_b128 v[156:159], v174 offset:17472
	ds_read_b128 v[160:163], v174 offset:17536
	ds_read_b128 v[164:167], v174 offset:17600
.Ltail3_r0:
	s_waitcnt lgkmcnt(0)
	v_mfma_f32_16x16x32_bf16 v[30:33], v[104:107], v[120:123], v[30:33]
	v_mfma_f32_16x16x32_bf16 v[26:29], v[104:107], v[136:139], v[26:29]
	v_mfma_f32_16x16x32_bf16 v[30:33], v[108:111], v[124:127], v[30:33]
	v_mfma_f32_16x16x32_bf16 v[26:29], v[108:111], v[140:143], v[26:29]
	v_mfma_f32_16x16x32_bf16 v[30:33], v[112:115], v[128:131], v[30:33]
	v_mfma_f32_16x16x32_bf16 v[26:29], v[112:115], v[144:147], v[26:29]
	v_mfma_f32_16x16x32_bf16 v[30:33], v[116:119], v[132:135], v[30:33]
	v_mfma_f32_16x16x32_bf16 v[26:29], v[116:119], v[148:151], v[26:29]
	s_andn2_b64 vcc, exec, s[10:11]
	s_cbranch_vccnz .Ltail3_m0
	v_mfma_f32_16x16x32_bf16 v[2:5], v[104:107], v[152:155], v[2:5]
	v_mfma_f32_16x16x32_bf16 v[2:5], v[108:111], v[156:159], v[2:5]
	v_mfma_f32_16x16x32_bf16 v[2:5], v[112:115], v[160:163], v[2:5]
	v_mfma_f32_16x16x32_bf16 v[2:5], v[116:119], v[164:167], v[2:5]
.Ltail3_m0:
	s_waitcnt vmcnt(5)
	s_cmpk_lt_u32 s12, 0x800
	s_cbranch_scc1 .Ltail3_w1
	s_waitcnt vmcnt(0)
.Ltail3_w1:
	ds_write_b128 v168, v[84:87] offset:21760
	s_and_saveexec_b64 s[6:7], s[0:1]
	ds_write_b128 v169, v[88:91] offset:21760
	s_or_b64 exec, exec, s[6:7]
	s_and_saveexec_b64 s[6:7], s[4:5]
	ds_write_b128 v170, v[92:95] offset:21760
	s_or_b64 exec, exec, s[6:7]
	ds_write_b128 v168, v[96:99] offset:60928
	ds_write_b128 v169, v[100:103] offset:60928
	s_cmpk_lt_u32 s12, 0x700
	s_cbranch_scc0 .Ltail3_np1
	v_lshl_add_u64 v[176:177], v[48:49], 0, s[12:13]
	global_load_dwordx4 v[84:87], v[176:177], off
	v_lshl_add_u64 v[176:177], v[50:51], 0, s[12:13]
	global_load_dwordx4 v[88:91], v[176:177], off
	v_lshl_add_u64 v[176:177], v[52:53], 0, s[12:13]
	global_load_dwordx4 v[92:95], v[176:177], off
	v_lshl_add_u64 v[176:177], v[54:55], 0, s[12:13]
	global_load_dwordx4 v[96:99], v[176:177], off
	v_lshl_add_u64 v[176:177], v[56:57], 0, s[12:13]
	global_load_dwordx4 v[100:103], v[176:177], off
.Ltail3_np1:
	s_add_u32 s12, s12, 0x100
	s_waitcnt lgkmcnt(0)
	s_barrier
	ds_read_b128 v[104:107], v171 offset:60928
	ds_read_b128 v[108:111], v171 offset:60992
	ds_read_b128 v[112:115], v171 offset:61056
	ds_read_b128 v[116:119], v171 offset:61120
	ds_read_b128 v[120:123], v172 offset:21760
	ds_read_b128 v[124:127], v172 offset:21824
	ds_read_b128 v[128:131], v172 offset:21888
	ds_read_b128 v[132:135], v172 offset:21952
	ds_read_b128 v[136:139], v173 offset:21760
	ds_read_b128 v[140:143], v173 offset:21824
	ds_read_b128 v[144:147], v173 offset:21888
	ds_read_b128 v[148:151], v173 offset:21952
	s_andn2_b64 vcc, exec, s[10:11]
	s_cbranch_vccnz .Ltail3_r1
	ds_read_b128 v[152:155], v174 offset:39168
	ds_read_b128 v[156:159], v174 offset:39232
	ds_read_b128 v[160:163], v174 offset:39296
	ds_read_b128 v[164:167], v174 offset:39360

.Ltail3_m1:
	s_cmpk_lt_u32 s12, 0x900
	s_cbranch_scc1 .Ltail3_loop
	s_movk_i32 s12, 0x800
	s_mov_b32 s13, 0
	s_movk_i32 s18, 0x8
	v_cndmask_b32_e64 v75, 0, 1, s[10:11]
	s_nop 1
	v_cmp_ne_u32_e64 s[6:7], 1, v75
	s_nop 7

.LBB0_3190:
.LBB0_3191:
	v_lshlrev_b32_e32 v77, 1, v163
	v_lshlrev_b32_e32 v176, 1, v59
	v_add_u32_e32 v178, v176, v67
	v_add_u32_e32 v177, v176, v66
	v_add_u32_e32 v176, v176, v65
	v_add_u32_e32 v179, v60, v77
	v_add_u32_e32 v180, v77, v69
	v_add_u32_e32 v181, v77, v71
	v_add_u32_e32 v182, v77, v72
	global_load_dwordx4 v[88:91], v[48:49], off
	global_load_dwordx4 v[92:95], v[50:51], off
	global_load_dwordx4 v[96:99], v[52:53], off
	global_load_dwordx4 v[100:103], v[54:55], off
	global_load_dwordx4 v[104:107], v[56:57], off
	s_mov_b32 s20, 0x100
	s_mov_b32 s21, 0
.Ltail4_loop:
	s_waitcnt vmcnt(5)
	ds_write_b128 v176, v[6:9] offset:0
	s_and_saveexec_b64 s[10:11], s[6:7]
	ds_write_b128 v177, v[10:13] offset:0
	s_or_b64 exec, exec, s[10:11]
	s_and_saveexec_b64 s[10:11], s[8:9]
	ds_write_b128 v178, v[14:17] offset:0
	s_or_b64 exec, exec, s[10:11]
	ds_write_b128 v176, v[18:21] offset:43520
	ds_write_b128 v177, v[22:25] offset:43520
	s_cmpk_lt_u32 s20, 0x700
	s_cbranch_scc0 .Ltail4_np0
	v_lshl_add_u64 v[184:185], v[48:49], 0, s[20:21]
	global_load_dwordx4 v[6:9], v[184:185], off
	v_lshl_add_u64 v[184:185], v[50:51], 0, s[20:21]
	global_load_dwordx4 v[10:13], v[184:185], off
	v_lshl_add_u64 v[184:185], v[52:53], 0, s[20:21]
	global_load_dwordx4 v[14:17], v[184:185], off
	v_lshl_add_u64 v[184:185], v[54:55], 0, s[20:21]
	global_load_dwordx4 v[18:21], v[184:185], off
	v_lshl_add_u64 v[184:185], v[56:57], 0, s[20:21]
	global_load_dwordx4 v[22:25], v[184:185], off
.Ltail4_np0:
	s_add_u32 s20, s20, 0x100
	s_waitcnt lgkmcnt(0)
	s_barrier
	ds_read_b128 v[108:111], v179 offset:43520
	ds_read_b128 v[112:115], v179 offset:43584
	ds_read_b128 v[116:119], v179 offset:43648
	ds_read_b128 v[120:123], v179 offset:43712
	ds_read_b128 v[124:127], v180 offset:0
	ds_read_b128 v[128:131], v180 offset:64
	ds_read_b128 v[132:135], v180 offset:128
	ds_read_b128 v[136:139], v180 offset:192
	ds_read_b128 v[140:143], v181 offset:0
	ds_read_b128 v[144:147], v181 offset:64
	ds_read_b128 v[148:151], v181 offset:128
	ds_read_b128 v[152:155], v181 offset:192
	s_andn2_b64 vcc, exec, s[16:17]
	s_cbranch_vccnz .Ltail4_r0
	ds_read_b128 v[156:159], v182 offset:17408
	ds_read_b128 v[164:167], v182 offset:17472
	ds_read_b128 v[168:171], v182 offset:17536
	ds_read_b128 v[172:175], v182 offset:17600
.Ltail4_r0:
	s_waitcnt lgkmcnt(0)
	v_mfma_f32_16x16x32_bf16 v[30:33], v[108:111], v[124:127], v[30:33]
	v_mfma_f32_16x16x32_bf16 v[26:29], v[108:111], v[140:143], v[26:29]
	v_mfma_f32_16x16x32_bf16 v[30:33], v[112:115], v[128:131], v[30:33]
	v_mfma_f32_16x16x32_bf16 v[26:29], v[112:115], v[144:147], v[26:29]
	v_mfma_f32_16x16x32_bf16 v[30:33], v[116:119], v[132:135], v[30:33]
	v_mfma_f32_16x16x32_bf16 v[26:29], v[116:119], v[148:151], v[26:29]
	v_mfma_f32_16x16x32_bf16 v[30:33], v[120:123], v[136:139], v[30:33]
	v_mfma_f32_16x16x32_bf16 v[26:29], v[120:123], v[152:155], v[26:29]
	s_andn2_b64 vcc, exec, s[16:17]
	s_cbranch_vccnz .Ltail4_m0
	v_mfma_f32_16x16x32_bf16 v[2:5], v[108:111], v[156:159], v[2:5]
	v_mfma_f32_16x16x32_bf16 v[2:5], v[112:115], v[164:167], v[2:5]
	v_mfma_f32_16x16x32_bf16 v[2:5], v[116:119], v[168:171], v[2:5]
	v_mfma_f32_16x16x32_bf16 v[2:5], v[120:123], v[172:175], v[2:5]
.Ltail4_m0:
	s_waitcnt vmcnt(5)
	s_cmpk_lt_u32 s20, 0x800
	s_cbranch_scc1 .Ltail4_w1
	s_waitcnt vmcnt(0)
.Ltail4_w1:
	ds_write_b128 v176, v[88:91] offset:21760
	s_and_saveexec_b64 s[10:11], s[6:7]
	ds_write_b128 v177, v[92:95] offset:21760
	s_or_b64 exec, exec, s[10:11]
	s_and_saveexec_b64 s[10:11], s[8:9]
	ds_write_b128 v178, v[96:99] offset:21760
	s_or_b64 exec, exec, s[10:11]
	ds_write_b128 v176, v[100:103] offset:60928
	ds_write_b128 v177, v[104:107] offset:60928
	s_cmpk_lt_u32 s20, 0x700
	s_cbranch_scc0 .Ltail4_np1
	v_lshl_add_u64 v[184:185], v[48:49], 0, s[20:21]
	global_load_dwordx4 v[88:91], v[184:185], off
	v_lshl_add_u64 v[184:185], v[50:51], 0, s[20:21]
	global_load_dwordx4 v[92:95], v[184:185], off
	v_lshl_add_u64 v[184:185], v[52:53], 0, s[20:21]
	global_load_dwordx4 v[96:99], v[184:185], off
	v_lshl_add_u64 v[184:185], v[54:55], 0, s[20:21]
	global_load_dwordx4 v[100:103], v[184:185], off
	v_lshl_add_u64 v[184:185], v[56:57], 0, s[20:21]
	global_load_dwordx4 v[104:107], v[184:185], off
.Ltail4_np1:
	s_add_u32 s20, s20, 0x100
	s_waitcnt lgkmcnt(0)
	s_barrier
	ds_read_b128 v[108:111], v179 offset:60928
	ds_read_b128 v[112:115], v179 offset:60992
	ds_read_b128 v[116:119], v179 offset:61056
	ds_read_b128 v[120:123], v179 offset:61120
	ds_read_b128 v[124:127], v180 offset:21760
	ds_read_b128 v[128:131], v180 offset:21824
	ds_read_b128 v[132:135], v180 offset:21888
	ds_read_b128 v[136:139], v180 offset:21952
	ds_read_b128 v[140:143], v181 offset:21760
	ds_read_b128 v[144:147], v181 offset:21824
	ds_read_b128 v[148:151], v181 offset:21888
	ds_read_b128 v[152:155], v181 offset:21952
	s_andn2_b64 vcc, exec, s[16:17]
	s_cbranch_vccnz .Ltail4_r1
	ds_read_b128 v[156:159], v182 offset:39168
	ds_read_b128 v[164:167], v182 offset:39232
	ds_read_b128 v[168:171], v182 offset:39296
	ds_read_b128 v[172:175], v182 offset:39360

.Ltail4_m1:
	s_cmpk_lt_u32 s20, 0x900
	s_cbranch_scc1 .Ltail4_loop
	s_movk_i32 s20, 0x800
	s_mov_b32 s21, 0
	s_movk_i32 s37, 0x8
	v_cndmask_b32_e64 v81, 0, 1, s[16:17]
	s_nop 1
	v_cmp_ne_u32_e64 s[10:11], 1, v81
	s_nop 7

.LBB0_3502:
.LBB0_3503:
	v_lshlrev_b32_e32 v180, 1, v58
	v_add_u32_e32 v182, v180, v66
	v_add_u32_e32 v181, v180, v65
	v_add_u32_e32 v180, v180, v64
	v_add_u32_e32 v183, v59, v73
	v_add_u32_e32 v184, v73, v68
	v_add_u32_e32 v185, v73, v70
	v_add_u32_e32 v186, v73, v71
	global_load_dwordx4 v[92:95], v[48:49], off
	global_load_dwordx4 v[96:99], v[50:51], off
	global_load_dwordx4 v[100:103], v[52:53], off
	global_load_dwordx4 v[104:107], v[54:55], off
	global_load_dwordx4 v[108:111], v[56:57], off
	s_mov_b32 s22, 0x100
	s_mov_b32 s23, 0
.Ltail5_loop:
	s_waitcnt vmcnt(5)
	ds_write_b128 v180, v[6:9] offset:0
	s_and_saveexec_b64 s[10:11], s[6:7]
	ds_write_b128 v181, v[10:13] offset:0
	s_or_b64 exec, exec, s[10:11]
	s_and_saveexec_b64 s[10:11], s[8:9]
	ds_write_b128 v182, v[14:17] offset:0
	s_or_b64 exec, exec, s[10:11]
	ds_write_b128 v180, v[18:21] offset:43520
	ds_write_b128 v181, v[22:25] offset:43520
	s_cmpk_lt_u32 s22, 0x1500
	s_cbranch_scc0 .Ltail5_np0
	v_lshl_add_u64 v[188:189], v[48:49], 0, s[22:23]
	global_load_dwordx4 v[6:9], v[188:189], off
	v_lshl_add_u64 v[188:189], v[50:51], 0, s[22:23]
	global_load_dwordx4 v[10:13], v[188:189], off
	v_lshl_add_u64 v[188:189], v[52:53], 0, s[22:23]
	global_load_dwordx4 v[14:17], v[188:189], off
	v_lshl_add_u64 v[188:189], v[54:55], 0, s[22:23]
	global_load_dwordx4 v[18:21], v[188:189], off
	v_lshl_add_u64 v[188:189], v[56:57], 0, s[22:23]
	global_load_dwordx4 v[22:25], v[188:189], off
.Ltail5_np0:
	s_add_u32 s22, s22, 0x100
	s_waitcnt lgkmcnt(0)
	s_barrier
	ds_read_b128 v[112:115], v183 offset:43520
	ds_read_b128 v[116:119], v183 offset:43584
	ds_read_b128 v[120:123], v183 offset:43648
	ds_read_b128 v[124:127], v183 offset:43712
	ds_read_b128 v[128:131], v184 offset:0
	ds_read_b128 v[132:135], v184 offset:64
	ds_read_b128 v[136:139], v184 offset:128
	ds_read_b128 v[144:147], v184 offset:192
	ds_read_b128 v[148:151], v185 offset:0
	ds_read_b128 v[152:155], v185 offset:64
	ds_read_b128 v[156:159], v185 offset:128
	ds_read_b128 v[160:163], v185 offset:192
	s_andn2_b64 vcc, exec, s[14:15]
	s_cbranch_vccnz .Ltail5_r0
	ds_read_b128 v[164:167], v186 offset:17408
	ds_read_b128 v[168:171], v186 offset:17472
	ds_read_b128 v[172:175], v186 offset:17536
	ds_read_b128 v[176:179], v186 offset:17600
.Ltail5_r0:
	s_waitcnt lgkmcnt(0)
	v_mfma_f32_16x16x32_bf16 v[30:33], v[112:115], v[128:131], v[30:33]
	v_mfma_f32_16x16x32_bf16 v[26:29], v[112:115], v[148:151], v[26:29]
	v_mfma_f32_16x16x32_bf16 v[30:33], v[116:119], v[132:135], v[30:33]
	v_mfma_f32_16x16x32_bf16 v[26:29], v[116:119], v[152:155], v[26:29]
	v_mfma_f32_16x16x32_bf16 v[30:33], v[120:123], v[136:139], v[30:33]
	v_mfma_f32_16x16x32_bf16 v[26:29], v[120:123], v[156:159], v[26:29]
	v_mfma_f32_16x16x32_bf16 v[30:33], v[124:127], v[144:147], v[30:33]
	v_mfma_f32_16x16x32_bf16 v[26:29], v[124:127], v[160:163], v[26:29]
	s_andn2_b64 vcc, exec, s[14:15]
	s_cbranch_vccnz .Ltail5_m0
	v_mfma_f32_16x16x32_bf16 v[2:5], v[112:115], v[164:167], v[2:5]
	v_mfma_f32_16x16x32_bf16 v[2:5], v[116:119], v[168:171], v[2:5]
	v_mfma_f32_16x16x32_bf16 v[2:5], v[120:123], v[172:175], v[2:5]
	v_mfma_f32_16x16x32_bf16 v[2:5], v[124:127], v[176:179], v[2:5]
.Ltail5_m0:
	s_waitcnt vmcnt(5)
	s_cmpk_lt_u32 s22, 0x1600
	s_cbranch_scc1 .Ltail5_w1
	s_waitcnt vmcnt(0)
.Ltail5_w1:
	ds_write_b128 v180, v[92:95] offset:21760
	s_and_saveexec_b64 s[10:11], s[6:7]
	ds_write_b128 v181, v[96:99] offset:21760
	s_or_b64 exec, exec, s[10:11]
	s_and_saveexec_b64 s[10:11], s[8:9]
	ds_write_b128 v182, v[100:103] offset:21760
	s_or_b64 exec, exec, s[10:11]
	ds_write_b128 v180, v[104:107] offset:60928
	ds_write_b128 v181, v[108:111] offset:60928
	s_cmpk_lt_u32 s22, 0x1500
	s_cbranch_scc0 .Ltail5_np1
	v_lshl_add_u64 v[188:189], v[48:49], 0, s[22:23]
	global_load_dwordx4 v[92:95], v[188:189], off
	v_lshl_add_u64 v[188:189], v[50:51], 0, s[22:23]
	global_load_dwordx4 v[96:99], v[188:189], off
	v_lshl_add_u64 v[188:189], v[52:53], 0, s[22:23]
	global_load_dwordx4 v[100:103], v[188:189], off
	v_lshl_add_u64 v[188:189], v[54:55], 0, s[22:23]
	global_load_dwordx4 v[104:107], v[188:189], off
	v_lshl_add_u64 v[188:189], v[56:57], 0, s[22:23]
	global_load_dwordx4 v[108:111], v[188:189], off
.Ltail5_np1:
	s_add_u32 s22, s22, 0x100
	s_waitcnt lgkmcnt(0)
	s_barrier
	ds_read_b128 v[112:115], v183 offset:60928
	ds_read_b128 v[116:119], v183 offset:60992
	ds_read_b128 v[120:123], v183 offset:61056
	ds_read_b128 v[124:127], v183 offset:61120
	ds_read_b128 v[128:131], v184 offset:21760
	ds_read_b128 v[132:135], v184 offset:21824
	ds_read_b128 v[136:139], v184 offset:21888
	ds_read_b128 v[144:147], v184 offset:21952
	ds_read_b128 v[148:151], v185 offset:21760
	ds_read_b128 v[152:155], v185 offset:21824
	ds_read_b128 v[156:159], v185 offset:21888
	ds_read_b128 v[160:163], v185 offset:21952
	s_andn2_b64 vcc, exec, s[14:15]
	s_cbranch_vccnz .Ltail5_r1
	ds_read_b128 v[164:167], v186 offset:39168
	ds_read_b128 v[168:171], v186 offset:39232
	ds_read_b128 v[172:175], v186 offset:39296
	ds_read_b128 v[176:179], v186 offset:39360

.Ltail5_m1:
	s_cmpk_lt_u32 s22, 0x1700
	s_cbranch_scc1 .Ltail5_loop
	s_movk_i32 s22, 0x1600
	s_mov_b32 s23, 0
	s_movk_i32 s42, 0x16
	v_cndmask_b32_e64 v82, 0, 1, s[14:15]
	s_nop 1
	v_cmp_ne_u32_e64 s[10:11], 1, v82
	s_nop 7

.LBB0_3539:
.LBB0_3540:
	v_lshlrev_b32_e32 v180, 1, v61
	v_add_u32_e32 v182, v180, v72
	v_add_u32_e32 v181, v180, v71
	v_add_u32_e32 v180, v180, v70
	v_add_u32_e32 v183, v62, v45
	v_add_u32_e32 v184, v45, v73
	v_add_u32_e32 v185, v45, v74
	v_add_u32_e32 v186, v45, v75
	global_load_dwordx4 v[92:95], v[50:51], off
	global_load_dwordx4 v[96:99], v[52:53], off
	global_load_dwordx4 v[100:103], v[54:55], off
	global_load_dwordx4 v[104:107], v[56:57], off
	global_load_dwordx4 v[108:111], v[58:59], off
	s_mov_b32 s14, 0x100
	s_mov_b32 s15, 0
.Ltail6_loop:
	s_waitcnt vmcnt(5)
	ds_write_b128 v180, v[6:9] offset:0
	s_and_saveexec_b64 s[12:13], s[8:9]
	ds_write_b128 v181, v[10:13] offset:0
	s_or_b64 exec, exec, s[12:13]
	s_and_saveexec_b64 s[12:13], s[10:11]
	ds_write_b128 v182, v[14:17] offset:0
	s_or_b64 exec, exec, s[12:13]
	ds_write_b128 v180, v[18:21] offset:43520
	ds_write_b128 v181, v[22:25] offset:43520
	s_cmpk_lt_u32 s14, 0x1500
	s_cbranch_scc0 .Ltail6_np0
	v_lshl_add_u64 v[188:189], v[50:51], 0, s[14:15]
	global_load_dwordx4 v[6:9], v[188:189], off
	v_lshl_add_u64 v[188:189], v[52:53], 0, s[14:15]
	global_load_dwordx4 v[10:13], v[188:189], off
	v_lshl_add_u64 v[188:189], v[54:55], 0, s[14:15]
	global_load_dwordx4 v[14:17], v[188:189], off
	v_lshl_add_u64 v[188:189], v[56:57], 0, s[14:15]
	global_load_dwordx4 v[18:21], v[188:189], off
	v_lshl_add_u64 v[188:189], v[58:59], 0, s[14:15]
	global_load_dwordx4 v[22:25], v[188:189], off
.Ltail6_np0:
	s_add_u32 s14, s14, 0x100
	s_waitcnt lgkmcnt(0)
	s_barrier
	ds_read_b128 v[112:115], v183 offset:43520
	ds_read_b128 v[116:119], v183 offset:43584
	ds_read_b128 v[120:123], v183 offset:43648
	ds_read_b128 v[124:127], v183 offset:43712
	ds_read_b128 v[128:131], v184 offset:0
	ds_read_b128 v[132:135], v184 offset:64
	ds_read_b128 v[136:139], v184 offset:128
	ds_read_b128 v[144:147], v184 offset:192
	ds_read_b128 v[148:151], v185 offset:0
	ds_read_b128 v[152:155], v185 offset:64
	ds_read_b128 v[156:159], v185 offset:128
	ds_read_b128 v[160:163], v185 offset:192
	s_andn2_b64 vcc, exec, s[20:21]
	s_cbranch_vccnz .Ltail6_r0
	ds_read_b128 v[164:167], v186 offset:17408
	ds_read_b128 v[168:171], v186 offset:17472
	ds_read_b128 v[172:175], v186 offset:17536
	ds_read_b128 v[176:179], v186 offset:17600
.Ltail6_r0:
	s_waitcnt lgkmcnt(0)
	v_mfma_f32_16x16x32_bf16 v[30:33], v[112:115], v[128:131], v[30:33]
	v_mfma_f32_16x16x32_bf16 v[26:29], v[112:115], v[148:151], v[26:29]
	v_mfma_f32_16x16x32_bf16 v[30:33], v[116:119], v[132:135], v[30:33]
	v_mfma_f32_16x16x32_bf16 v[26:29], v[116:119], v[152:155], v[26:29]
	v_mfma_f32_16x16x32_bf16 v[30:33], v[120:123], v[136:139], v[30:33]
	v_mfma_f32_16x16x32_bf16 v[26:29], v[120:123], v[156:159], v[26:29]
	v_mfma_f32_16x16x32_bf16 v[30:33], v[124:127], v[144:147], v[30:33]
	v_mfma_f32_16x16x32_bf16 v[26:29], v[124:127], v[160:163], v[26:29]
	s_andn2_b64 vcc, exec, s[20:21]
	s_cbranch_vccnz .Ltail6_m0
	v_mfma_f32_16x16x32_bf16 v[2:5], v[112:115], v[164:167], v[2:5]
	v_mfma_f32_16x16x32_bf16 v[2:5], v[116:119], v[168:171], v[2:5]
	v_mfma_f32_16x16x32_bf16 v[2:5], v[120:123], v[172:175], v[2:5]
	v_mfma_f32_16x16x32_bf16 v[2:5], v[124:127], v[176:179], v[2:5]
.Ltail6_m0:
	s_waitcnt vmcnt(5)
	s_cmpk_lt_u32 s14, 0x1600
	s_cbranch_scc1 .Ltail6_w1
	s_waitcnt vmcnt(0)
.Ltail6_w1:
	ds_write_b128 v180, v[92:95] offset:21760
	s_and_saveexec_b64 s[12:13], s[8:9]
	ds_write_b128 v181, v[96:99] offset:21760
	s_or_b64 exec, exec, s[12:13]
	s_and_saveexec_b64 s[12:13], s[10:11]
	ds_write_b128 v182, v[100:103] offset:21760
	s_or_b64 exec, exec, s[12:13]
	ds_write_b128 v180, v[104:107] offset:60928
	ds_write_b128 v181, v[108:111] offset:60928
	s_cmpk_lt_u32 s14, 0x1500
	s_cbranch_scc0 .Ltail6_np1
	v_lshl_add_u64 v[188:189], v[50:51], 0, s[14:15]
	global_load_dwordx4 v[92:95], v[188:189], off
	v_lshl_add_u64 v[188:189], v[52:53], 0, s[14:15]
	global_load_dwordx4 v[96:99], v[188:189], off
	v_lshl_add_u64 v[188:189], v[54:55], 0, s[14:15]
	global_load_dwordx4 v[100:103], v[188:189], off
	v_lshl_add_u64 v[188:189], v[56:57], 0, s[14:15]
	global_load_dwordx4 v[104:107], v[188:189], off
	v_lshl_add_u64 v[188:189], v[58:59], 0, s[14:15]
	global_load_dwordx4 v[108:111], v[188:189], off
.Ltail6_np1:
	s_add_u32 s14, s14, 0x100
	s_waitcnt lgkmcnt(0)
	s_barrier
	ds_read_b128 v[112:115], v183 offset:60928
	ds_read_b128 v[116:119], v183 offset:60992
	ds_read_b128 v[120:123], v183 offset:61056
	ds_read_b128 v[124:127], v183 offset:61120
	ds_read_b128 v[128:131], v184 offset:21760
	ds_read_b128 v[132:135], v184 offset:21824
	ds_read_b128 v[136:139], v184 offset:21888
	ds_read_b128 v[144:147], v184 offset:21952
	ds_read_b128 v[148:151], v185 offset:21760
	ds_read_b128 v[152:155], v185 offset:21824
	ds_read_b128 v[156:159], v185 offset:21888
	ds_read_b128 v[160:163], v185 offset:21952
	s_andn2_b64 vcc, exec, s[20:21]
	s_cbranch_vccnz .Ltail6_r1
	ds_read_b128 v[164:167], v186 offset:39168
	ds_read_b128 v[168:171], v186 offset:39232
	ds_read_b128 v[172:175], v186 offset:39296
	ds_read_b128 v[176:179], v186 offset:39360

.Ltail6_m1:
	s_cmpk_lt_u32 s14, 0x1700
	s_cbranch_scc1 .Ltail6_loop
	s_movk_i32 s14, 0x1600
	s_mov_b32 s15, 0
	s_movk_i32 s37, 0x16
	v_cndmask_b32_e64 v86, 0, 1, s[20:21]
	s_nop 1
	v_cmp_ne_u32_e64 s[12:13], 1, v86
	s_nop 7
